# stack of small edits on v40: scores-store address arithmetic 128->10 VALU per tile, conversion chunks de-serialised, P5 prefix batched, attention output dwordx4 stores
# speedup vs baseline: 1.0042x; 1.0042x over previous
; DEV unsigned pk2(float lo, float hi) { f32x2_t v = {lo, hi}; bf16x2_t b = __builtin_convertvector(v, bf16x2_t); return __builtin_bit_cast(unsigned, b); }
; DEV void attn_unit(const Params& P, int b, int qb, int h) {
;     ...
;   if (g == 0) {
;     const float m1 = mg[32], l1 = mg[33];
;     const float ms = fmaxf(m, m1);
;     const float f0 = __builtin_amdgcn_exp2f(m - ms), f1 = __builtin_amdgcn_exp2f(m1 - ms);
;     l = l * f0 + l1 * f1;
; #pragma unroll
;     for (int r = 0; r < 16; ++r) { o[0][r] = o[0][r] * f0 + mg[r] * f1; o[1][r] = o[1][r] * f0 + mg[16 + r] * f1; }
;     l += __shfl_xor(l, 32);
;     const float inv = 1.f / l;
; #pragma unroll
;     for (int db = 0; db < 2; ++db)
; #pragma unroll
;       for (int rq = 0; rq < 4; ++rq) {
;         u32x2 ov; ov[0] = pk2(o[db][4 * rq] * inv, o[db][4 * rq + 1] * inv); ov[1] = pk2(o[db][4 * rq + 2] * inv, o[db][4 * rq + 3] * inv);
;         *(u32x2*)(ycat + (size_t)tokq * DM + 512 + h * 64 + 32 * db + 8 * rq + 4 * hi) = ov;
;       }
.LBB0_195:
	s_or_b64 exec, exec, s[6:7]
	v_cmp_gt_u32_e32 vcc, s34, v119
	s_waitcnt lgkmcnt(0)
	s_barrier
	s_and_saveexec_b64 s[6:7], vcc
	s_xor_b64 s[6:7], exec, s[6:7]
	s_cbranch_execz .LBB0_153
	ds_read_b64 v[34:35], v32 offset:128
	v_max_f32_e32 v33, v125, v125
	v_lshlrev_b64 v[38:39], 11, v[112:113]
	v_lshl_add_u64 v[38:39], s[82:83], 0, v[38:39]
	v_mov_b32_e32 v119, v113
	s_waitcnt lgkmcnt(0)
	v_max_f32_e32 v36, v34, v34
	v_max_f32_e32 v33, v33, v36
	v_sub_f32_e32 v36, v125, v33
	v_sub_f32_e32 v33, v34, v33
	v_exp_f32_e32 v42, v36
	v_exp_f32_e32 v125, v33
	v_mov_b32_e32 v43, v35
	v_lshl_add_u64 v[38:39], v[114:115], 1, v[38:39]
	v_lshl_add_u64 v[44:45], v[38:39], 0, v[118:119]
	v_pk_mul_f32 v[34:35], v[124:125], v[42:43]
	v_mov_b32_e32 v50, v125
	v_add_f32_e32 v33, v34, v35
	ds_bpermute_b32 v40, v155, v33
	ds_read2_b64 v[34:37], v32 offset1:1
	v_lshl_add_u64 v[48:49], v[44:45], 0, s[16:17]
	s_waitcnt lgkmcnt(1)
	v_add_f32_e32 v33, v33, v40
	v_div_scale_f32 v40, s[8:9], v33, v33, 1.0
	v_rcp_f32_e32 v41, v40
	v_div_scale_f32 v38, vcc, 1.0, v33, 1.0
	v_fma_f32 v39, -v40, v41, 1.0
	v_fmac_f32_e32 v41, v39, v41
	v_mul_f32_e32 v39, v38, v41
	v_fma_f32 v43, -v40, v39, v38
	v_fmac_f32_e32 v39, v43, v41
	v_fma_f32 v38, -v40, v39, v38
	v_div_fmas_f32 v38, v38, v41, v39
	v_div_fixup_f32 v46, v38, v33, 1.0
	ds_read2_b64 v[38:41], v32 offset0:2 offset1:3
	s_waitcnt lgkmcnt(1)
	v_pk_mul_f32 v[34:35], v[34:35], v[50:51] op_sel_hi:[1,0]
	s_nop 0
	v_pk_fma_f32 v[16:17], v[16:17], v[42:43], v[34:35] op_sel_hi:[1,0,1]
	v_pk_mul_f32 v[34:35], v[50:51], v[36:37] op_sel_hi:[0,1]
	v_pk_fma_f32 v[18:19], v[18:19], v[42:43], v[34:35] op_sel_hi:[1,0,1]
	v_pk_mul_f32 v[16:17], v[16:17], v[46:47] op_sel_hi:[1,0]
	v_pk_mul_f32 v[18:19], v[18:19], v[46:47] op_sel_hi:[1,0]
	v_cvt_pk_bf16_f32 v236, v16, v17
	v_cvt_pk_bf16_f32 v237, v18, v19
	v_add_co_u32_e32 v18, vcc, s35, v44
	s_nop 1
	v_addc_co_u32_e32 v19, vcc, 0, v45, vcc
	s_waitcnt lgkmcnt(0)
	v_pk_mul_f32 v[16:17], v[50:51], v[38:39] op_sel_hi:[0,1]
	v_pk_fma_f32 v[16:17], v[20:21], v[42:43], v[16:17] op_sel_hi:[1,0,1]
	s_nop 0
	v_pk_mul_f32 v[16:17], v[16:17], v[46:47] op_sel_hi:[1,0]
	s_nop 0
	v_cvt_pk_bf16_f32 v238, v16, v17
	v_pk_mul_f32 v[16:17], v[50:51], v[40:41] op_sel_hi:[0,1]
	v_pk_fma_f32 v[22:23], v[22:23], v[42:43], v[16:17] op_sel_hi:[1,0,1]
	ds_read2_b64 v[16:19], v32 offset0:4 offset1:5
	v_pk_mul_f32 v[22:23], v[22:23], v[46:47] op_sel_hi:[1,0]
	s_nop 0
	v_cvt_pk_bf16_f32 v239, v22, v23
	ds_read2_b64 v[20:23], v32 offset0:6 offset1:7
	s_waitcnt lgkmcnt(1)
	v_pk_mul_f32 v[16:17], v[50:51], v[16:17] op_sel_hi:[0,1]
	v_pk_mul_f32 v[18:19], v[50:51], v[18:19] op_sel_hi:[0,1]
	v_pk_fma_f32 v[16:17], v[24:25], v[42:43], v[16:17] op_sel_hi:[1,0,1]
	v_pk_fma_f32 v[18:19], v[26:27], v[42:43], v[18:19] op_sel_hi:[1,0,1]
	v_pk_mul_f32 v[16:17], v[16:17], v[46:47] op_sel_hi:[1,0]
	v_pk_mul_f32 v[18:19], v[18:19], v[46:47] op_sel_hi:[1,0]
	v_cvt_pk_bf16_f32 v240, v16, v17
	v_cvt_pk_bf16_f32 v241, v18, v19
	s_waitcnt lgkmcnt(0)
	v_pk_mul_f32 v[16:17], v[50:51], v[20:21] op_sel_hi:[0,1]
	v_pk_fma_f32 v[16:17], v[28:29], v[42:43], v[16:17] op_sel_hi:[1,0,1]
	s_nop 0
	v_pk_mul_f32 v[16:17], v[16:17], v[46:47] op_sel_hi:[1,0]
	s_nop 0
	v_cvt_pk_bf16_f32 v242, v16, v17
	v_pk_mul_f32 v[16:17], v[50:51], v[22:23] op_sel_hi:[0,1]
	v_pk_fma_f32 v[22:23], v[30:31], v[42:43], v[16:17] op_sel_hi:[1,0,1]
	ds_read2_b64 v[16:19], v32 offset0:8 offset1:9
	v_pk_mul_f32 v[22:23], v[22:23], v[46:47] op_sel_hi:[1,0]
	s_nop 0
	v_cvt_pk_bf16_f32 v243, v22, v23
	ds_read2_b64 v[20:23], v32 offset0:10 offset1:11
	s_waitcnt lgkmcnt(1)
	v_pk_mul_f32 v[16:17], v[16:17], v[50:51] op_sel_hi:[1,0]
	s_nop 0
	v_pk_fma_f32 v[0:1], v[0:1], v[42:43], v[16:17] op_sel_hi:[1,0,1]
	v_pk_mul_f32 v[16:17], v[50:51], v[18:19] op_sel_hi:[0,1]
	v_pk_fma_f32 v[2:3], v[2:3], v[42:43], v[16:17] op_sel_hi:[1,0,1]
	v_pk_mul_f32 v[0:1], v[0:1], v[46:47] op_sel_hi:[1,0]
	v_pk_mul_f32 v[2:3], v[2:3], v[46:47] op_sel_hi:[1,0]
	v_cvt_pk_bf16_f32 v244, v0, v1
	v_cvt_pk_bf16_f32 v245, v2, v3
	s_waitcnt lgkmcnt(0)
	v_pk_mul_f32 v[0:1], v[50:51], v[20:21] op_sel_hi:[0,1]
	v_pk_fma_f32 v[0:1], v[4:5], v[42:43], v[0:1] op_sel_hi:[1,0,1]
	s_nop 0
	v_pk_mul_f32 v[0:1], v[0:1], v[46:47] op_sel_hi:[1,0]
	s_nop 0
	v_cvt_pk_bf16_f32 v246, v0, v1
	v_pk_mul_f32 v[0:1], v[50:51], v[22:23] op_sel_hi:[0,1]
	v_pk_fma_f32 v[6:7], v[6:7], v[42:43], v[0:1] op_sel_hi:[1,0,1]
	ds_read2_b64 v[0:3], v32 offset0:12 offset1:13
	v_pk_mul_f32 v[6:7], v[6:7], v[46:47] op_sel_hi:[1,0]
	s_nop 0
	v_cvt_pk_bf16_f32 v247, v6, v7
	ds_read2_b64 v[4:7], v32 offset0:14 offset1:15
	s_waitcnt lgkmcnt(1)
	v_pk_mul_f32 v[0:1], v[50:51], v[0:1] op_sel_hi:[0,1]
	v_pk_mul_f32 v[2:3], v[50:51], v[2:3] op_sel_hi:[0,1]
	v_pk_fma_f32 v[0:1], v[8:9], v[42:43], v[0:1] op_sel_hi:[1,0,1]
	v_pk_fma_f32 v[2:3], v[10:11], v[42:43], v[2:3] op_sel_hi:[1,0,1]
	v_pk_mul_f32 v[0:1], v[0:1], v[46:47] op_sel_hi:[1,0]
	v_pk_mul_f32 v[2:3], v[2:3], v[46:47] op_sel_hi:[1,0]
	v_cvt_pk_bf16_f32 v248, v0, v1
	v_cvt_pk_bf16_f32 v249, v2, v3
	s_waitcnt lgkmcnt(0)
	v_pk_mul_f32 v[0:1], v[50:51], v[4:5] op_sel_hi:[0,1]
	v_pk_mul_f32 v[2:3], v[50:51], v[6:7] op_sel_hi:[0,1]
	v_pk_fma_f32 v[0:1], v[12:13], v[42:43], v[0:1] op_sel_hi:[1,0,1]
	v_pk_fma_f32 v[2:3], v[14:15], v[42:43], v[2:3] op_sel_hi:[1,0,1]
	v_pk_mul_f32 v[0:1], v[0:1], v[46:47] op_sel_hi:[1,0]
	v_pk_mul_f32 v[2:3], v[2:3], v[46:47] op_sel_hi:[1,0]
	v_cvt_pk_bf16_f32 v250, v0, v1
	v_cvt_pk_bf16_f32 v251, v2, v3
	v_mbcnt_lo_u32_b32 v252, -1, 0
	v_mbcnt_hi_u32_b32 v252, -1, v252
	v_and_b32_e32 v252, 32, v252
	v_lshrrev_b32_e32 v252, 2, v252
	v_mov_b32_e32 v253, 0
	v_lshl_add_u64 v[254:255], v[48:49], 0, v[252:253]
	v_permlane32_swap_b32_e32 v236, v238
	v_permlane32_swap_b32_e32 v237, v239
	global_store_dwordx4 v[254:255], v[236:239], off
	v_permlane32_swap_b32_e32 v240, v242
	v_permlane32_swap_b32_e32 v241, v243
	global_store_dwordx4 v[254:255], v[240:243], off offset:32
	v_permlane32_swap_b32_e32 v244, v246
	v_permlane32_swap_b32_e32 v245, v247
	global_store_dwordx4 v[254:255], v[244:247], off offset:64
	v_permlane32_swap_b32_e32 v248, v250
	v_permlane32_swap_b32_e32 v249, v251
	global_store_dwordx4 v[254:255], v[248:251], off offset:96
	s_branch .LBB0_153

; #define FOR_ACC _Pragma("unroll") for (int nb = 0; nb < 2; ++nb) _Pragma("unroll") for (int mb = 0; mb < 2; ++mb) _Pragma("unroll") for (int rq = 0; rq < 4; ++rq)
; DEV void chain_peer_ple(const Params& P, int l, int p) {
;     ...
;     gemm_seq<63, 63>(4, [&](int nt) { return GTile{hn + (size_t)m0 * DM, DM, wpt + (size_t)((hg * 4 + nt) * 256) * DM, DM, DM}; }, [&](int nt, f32x16 (&acc)[2][2], int) {
;       FOR_ACC {
;         const int tr = 64 * wm + 32 * mb + l32, col = nt * 256 + 64 * wn + 32 * nb + 8 * rq + 4 * hi;
; #pragma unroll
;         for (int e = 0; e < 4; ++e) scoresT[(size_t)(col + e) * 128 + tr] = acc[nb][mb][4 * rq + e];
;       }
.LBB0_294:
	v_lshl_add_u32 v66, s15, 8, v78
	v_ashrrev_i32_e32 v67, 31, v66
	v_lshlrev_b64 v[68:69], 9, v[66:67]
	v_lshl_add_u64 v[68:69], v[64:65], 0, v[68:69]
	s_mov_b64 s[98:99], 0x1000
	flat_store_dword v[68:69], v48
	flat_store_dword v[68:69], v49 offset:512
	flat_store_dword v[68:69], v50 offset:1024
	flat_store_dword v[68:69], v51 offset:1536
	flat_store_dword v[68:69], v32 offset:128
	flat_store_dword v[68:69], v33 offset:640
	flat_store_dword v[68:69], v34 offset:1152
	flat_store_dword v[68:69], v35 offset:1664
	v_lshl_add_u64 v[68:69], v[68:69], 0, s[98:99]
	flat_store_dword v[68:69], v52
	flat_store_dword v[68:69], v53 offset:512
	flat_store_dword v[68:69], v54 offset:1024
	flat_store_dword v[68:69], v55 offset:1536
	flat_store_dword v[68:69], v36 offset:128
	flat_store_dword v[68:69], v37 offset:640
	flat_store_dword v[68:69], v38 offset:1152
	flat_store_dword v[68:69], v39 offset:1664
	v_lshl_add_u64 v[68:69], v[68:69], 0, s[98:99]
	flat_store_dword v[68:69], v56
	flat_store_dword v[68:69], v57 offset:512
	flat_store_dword v[68:69], v58 offset:1024
	flat_store_dword v[68:69], v59 offset:1536
	flat_store_dword v[68:69], v40 offset:128
	flat_store_dword v[68:69], v41 offset:640
	flat_store_dword v[68:69], v42 offset:1152
	flat_store_dword v[68:69], v43 offset:1664
	v_lshl_add_u64 v[68:69], v[68:69], 0, s[98:99]
	flat_store_dword v[68:69], v60
	flat_store_dword v[68:69], v61 offset:512
	flat_store_dword v[68:69], v62 offset:1024
	flat_store_dword v[68:69], v63 offset:1536
	flat_store_dword v[68:69], v44 offset:128
	flat_store_dword v[68:69], v45 offset:640
	flat_store_dword v[68:69], v46 offset:1152
	flat_store_dword v[68:69], v47 offset:1664
	v_lshl_add_u64 v[68:69], v[68:69], 0, s[98:99]
	flat_store_dword v[68:69], v16
	flat_store_dword v[68:69], v17 offset:512
	flat_store_dword v[68:69], v18 offset:1024
	flat_store_dword v[68:69], v19 offset:1536
	flat_store_dword v[68:69], v0 offset:128
	flat_store_dword v[68:69], v1 offset:640
	flat_store_dword v[68:69], v2 offset:1152
	flat_store_dword v[68:69], v3 offset:1664
	v_lshl_add_u64 v[68:69], v[68:69], 0, s[98:99]
	flat_store_dword v[68:69], v20
	flat_store_dword v[68:69], v21 offset:512
	flat_store_dword v[68:69], v22 offset:1024
	flat_store_dword v[68:69], v23 offset:1536
	flat_store_dword v[68:69], v4 offset:128
	flat_store_dword v[68:69], v5 offset:640
	flat_store_dword v[68:69], v6 offset:1152
	flat_store_dword v[68:69], v7 offset:1664
	v_lshl_add_u64 v[68:69], v[68:69], 0, s[98:99]
	flat_store_dword v[68:69], v24
	flat_store_dword v[68:69], v25 offset:512
	flat_store_dword v[68:69], v26 offset:1024
	flat_store_dword v[68:69], v27 offset:1536
	flat_store_dword v[68:69], v8 offset:128
	flat_store_dword v[68:69], v9 offset:640
	flat_store_dword v[68:69], v10 offset:1152
	flat_store_dword v[68:69], v11 offset:1664
	v_lshl_add_u64 v[68:69], v[68:69], 0, s[98:99]
	flat_store_dword v[68:69], v28
	flat_store_dword v[68:69], v29 offset:512
	flat_store_dword v[68:69], v30 offset:1024
	flat_store_dword v[68:69], v31 offset:1536
	flat_store_dword v[68:69], v12 offset:128
	flat_store_dword v[68:69], v13 offset:640
	flat_store_dword v[68:69], v14 offset:1152
	flat_store_dword v[68:69], v15 offset:1664
	s_cmp_lg_u32 s0, 4
	s_mov_b32 s15, s0
	s_cbranch_scc0 .LBB0_292

; #define FOR_ACC _Pragma("unroll") for (int nb = 0; nb < 2; ++nb) _Pragma("unroll") for (int mb = 0; mb < 2; ++mb) _Pragma("unroll") for (int rq = 0; rq < 4; ++rq)
; DEV void chain_peer_ple(const Params& P, int l, int p) {
;     ...
;       FOR_ACC {
;         const int tr = 64 * wm + 32 * mb + l32, col = nt * 256 + 64 * wn + 32 * nb + 8 * rq + 4 * hi;
; #pragma unroll
;         for (int e = 0; e < 4; ++e) scoresT[(size_t)(col + e) * 128 + tr] = acc[nb][mb][4 * rq + e];
;       }
.LBB0_733:
	v_lshl_add_u32 v66, s17, 8, v78
	v_ashrrev_i32_e32 v67, 31, v66
	v_lshlrev_b64 v[68:69], 9, v[66:67]
	v_lshl_add_u64 v[68:69], v[64:65], 0, v[68:69]
	s_mov_b64 s[98:99], 0x1000
	flat_store_dword v[68:69], v48
	flat_store_dword v[68:69], v49 offset:512
	flat_store_dword v[68:69], v50 offset:1024
	flat_store_dword v[68:69], v51 offset:1536
	flat_store_dword v[68:69], v32 offset:128
	flat_store_dword v[68:69], v33 offset:640
	flat_store_dword v[68:69], v34 offset:1152
	flat_store_dword v[68:69], v35 offset:1664
	v_lshl_add_u64 v[68:69], v[68:69], 0, s[98:99]
	flat_store_dword v[68:69], v52
	flat_store_dword v[68:69], v53 offset:512
	flat_store_dword v[68:69], v54 offset:1024
	flat_store_dword v[68:69], v55 offset:1536
	flat_store_dword v[68:69], v36 offset:128
	flat_store_dword v[68:69], v37 offset:640
	flat_store_dword v[68:69], v38 offset:1152
	flat_store_dword v[68:69], v39 offset:1664
	v_lshl_add_u64 v[68:69], v[68:69], 0, s[98:99]
	flat_store_dword v[68:69], v56
	flat_store_dword v[68:69], v57 offset:512
	flat_store_dword v[68:69], v58 offset:1024
	flat_store_dword v[68:69], v59 offset:1536
	flat_store_dword v[68:69], v40 offset:128
	flat_store_dword v[68:69], v41 offset:640
	flat_store_dword v[68:69], v42 offset:1152
	flat_store_dword v[68:69], v43 offset:1664
	v_lshl_add_u64 v[68:69], v[68:69], 0, s[98:99]
	flat_store_dword v[68:69], v60
	flat_store_dword v[68:69], v61 offset:512
	flat_store_dword v[68:69], v62 offset:1024
	flat_store_dword v[68:69], v63 offset:1536
	flat_store_dword v[68:69], v44 offset:128
	flat_store_dword v[68:69], v45 offset:640
	flat_store_dword v[68:69], v46 offset:1152
	flat_store_dword v[68:69], v47 offset:1664
	v_lshl_add_u64 v[68:69], v[68:69], 0, s[98:99]
	flat_store_dword v[68:69], v16
	flat_store_dword v[68:69], v17 offset:512
	flat_store_dword v[68:69], v18 offset:1024
	flat_store_dword v[68:69], v19 offset:1536
	flat_store_dword v[68:69], v0 offset:128
	flat_store_dword v[68:69], v1 offset:640
	flat_store_dword v[68:69], v2 offset:1152
	flat_store_dword v[68:69], v3 offset:1664
	v_lshl_add_u64 v[68:69], v[68:69], 0, s[98:99]
	flat_store_dword v[68:69], v20
	flat_store_dword v[68:69], v21 offset:512
	flat_store_dword v[68:69], v22 offset:1024
	flat_store_dword v[68:69], v23 offset:1536
	flat_store_dword v[68:69], v4 offset:128
	flat_store_dword v[68:69], v5 offset:640
	flat_store_dword v[68:69], v6 offset:1152
	flat_store_dword v[68:69], v7 offset:1664
	v_lshl_add_u64 v[68:69], v[68:69], 0, s[98:99]
	flat_store_dword v[68:69], v24
	flat_store_dword v[68:69], v25 offset:512
	flat_store_dword v[68:69], v26 offset:1024
	flat_store_dword v[68:69], v27 offset:1536
	flat_store_dword v[68:69], v8 offset:128
	flat_store_dword v[68:69], v9 offset:640
	flat_store_dword v[68:69], v10 offset:1152
	flat_store_dword v[68:69], v11 offset:1664
	v_lshl_add_u64 v[68:69], v[68:69], 0, s[98:99]
	flat_store_dword v[68:69], v28
	flat_store_dword v[68:69], v29 offset:512
	flat_store_dword v[68:69], v30 offset:1024
	flat_store_dword v[68:69], v31 offset:1536
	flat_store_dword v[68:69], v12 offset:128
	flat_store_dword v[68:69], v13 offset:640
	flat_store_dword v[68:69], v14 offset:1152
	flat_store_dword v[68:69], v15 offset:1664
	s_cmp_lg_u32 s2, 4
	s_mov_b32 s17, s2
	s_cbranch_scc0 .LBB0_731
